# ROW2 and ROW3: rows after the first come from per-wave-index ticket counters (dynamic row scheduling) instead of the static stride
# speedup vs baseline: 1.0111x; 1.0111x over previous
.LBB0_1623:
	v_lshrrev_b32_e32 v0, 6, v128
	s_waitcnt vmcnt(0)
	v_lshl_add_u32 v130, s34, 3, v0
	v_lshlrev_b32_e32 v236, 8, v0
	v_add_u32_e32 v236, 0x2480, v236
	s_lshl_b32 s82, s34, 3
	s_movk_i32 s0, 0x2400
	v_cmp_gt_i32_e32 vcc, s0, v130
	s_and_saveexec_b64 s[0:1], vcc
	s_cbranch_execz .LBB0_1626
	v_mbcnt_lo_u32_b32 v1, -1, 0
	v_mbcnt_hi_u32_b32 v1, -1, v1
	v_and_b32_e32 v2, 64, v1
	v_add_u32_e32 v2, 64, v2
	v_xor_b32_e32 v3, 1, v1
	v_cmp_lt_i32_e32 vcc, v3, v2
	v_ashrrev_i32_e32 v131, 31, v130
	v_lshlrev_b64 v[16:17], 12, v[130:131]
	v_cndmask_b32_e32 v3, v1, v3, vcc
	v_lshlrev_b32_e32 v129, 2, v3
	v_xor_b32_e32 v3, 2, v1
	v_cmp_lt_i32_e32 vcc, v3, v2
	s_mov_b64 s[6:7], 0x1ce05e00
	s_lshl_b32 s2, s94, 3
	v_cndmask_b32_e32 v3, v1, v3, vcc
	v_lshlrev_b32_e32 v184, 2, v3
	v_xor_b32_e32 v3, 4, v1
	v_cmp_lt_i32_e32 vcc, v3, v2
	v_lshlrev_b32_e32 v0, 2, v128
	s_add_u32 s12, s50, 0xc604000
	v_cndmask_b32_e32 v3, v1, v3, vcc
	v_lshlrev_b32_e32 v185, 2, v3
	v_xor_b32_e32 v3, 8, v1
	v_cmp_lt_i32_e32 vcc, v3, v2
	v_and_b32_e32 v0, 0xfc, v0
	s_addc_u32 s13, s51, 0
	v_cndmask_b32_e32 v3, v1, v3, vcc
	v_lshlrev_b32_e32 v186, 2, v3
	v_xor_b32_e32 v3, 16, v1
	v_cmp_lt_i32_e32 vcc, v3, v2
	v_mov_b32_e32 v133, 0
	v_or_b32_e32 v4, 0x200, v0
	v_cndmask_b32_e32 v3, v1, v3, vcc
	v_lshlrev_b32_e32 v187, 2, v3
	v_xor_b32_e32 v3, 32, v1
	v_cmp_lt_i32_e32 vcc, v3, v2
	v_or_b32_e32 v2, 0x100, v0
	v_or_b32_e32 v6, 0x300, v0
	v_cndmask_b32_e32 v1, v1, v3, vcc
	v_lshlrev_b32_e32 v188, 2, v1
	v_and_b32_e32 v1, 63, v128
	v_lshl_or_b32 v16, v1, 3, v16
	v_lshl_add_u64 v[16:17], s[50:51], 0, v[16:17]
	v_lshl_add_u64 v[134:135], v[16:17], 0, s[6:7]
	v_lshlrev_b64 v[16:17], 13, v[130:131]
	v_lshl_or_b32 v16, v1, 4, v16
	v_or_b32_e32 v8, 0x400, v0
	v_or_b32_e32 v10, 0x500, v0
	v_or_b32_e32 v12, 0x600, v0
	v_or_b32_e32 v14, 0x700, v0
	s_ashr_i32 s3, s2, 31
	v_lshl_add_u64 v[16:17], s[48:49], 0, v[16:17]
	s_mov_b64 s[8:9], 0x1000
	s_lshl_b64 s[6:7], s[2:3], 12
	v_lshl_add_u64 v[136:137], v[16:17], 0, s[8:9]
	s_lshl_b64 s[8:9], s[2:3], 13
	s_mov_b64 s[10:11], 0
	s_movk_i32 s3, 0x2000
	s_mov_b32 s18, 0x12000
	v_mov_b64_e32 v[138:139], s[12:13]
	s_mov_b64 s[12:13], 0xa000
	s_mov_b32 s19, 0xf3100000
	s_mov_b32 s20, 0xf5500000
	s_mov_b32 s21, 0xfdc00000
	v_lshlrev_b32_e32 v132, 2, v0
	v_lshlrev_b32_e32 v140, 2, v2
	v_mov_b32_e32 v141, v133
	v_lshlrev_b32_e32 v142, 2, v4
	v_mov_b32_e32 v143, v133
	v_lshlrev_b32_e32 v144, 2, v6
	v_mov_b32_e32 v145, v133
	v_lshlrev_b32_e32 v146, 2, v8
	v_mov_b32_e32 v147, v133
	v_lshlrev_b32_e32 v148, 2, v10
	v_mov_b32_e32 v149, v133
	v_lshlrev_b32_e32 v150, 2, v12
	v_mov_b32_e32 v151, v133
	v_lshlrev_b32_e32 v152, 2, v14
	v_mov_b32_e32 v153, v133
	s_mov_b64 s[14:15], 0xe000
	s_mov_b64 s[16:17], 0xc000
	v_mov_b32_e32 v131, 0x358637bd
	s_mov_b32 s22, 0x800000
	s_mov_b32 s23, 0xf0d00000
	s_movk_i32 s24, 0x23ff
.LBB0_1625:
	s_mov_b64 s[80:81], exec
	s_mov_b64 exec, 1
	v_mov_b32_e32 v237, 1
	global_atomic_add v237, v236, v237, s[50:51] sc0
	s_mov_b64 exec, s[80:81]
	global_load_dwordx4 v[28:31], v[136:137], off offset:-4096
	global_load_dwordx4 v[24:27], v[136:137], off offset:-3072
	global_load_dwordx4 v[20:23], v[136:137], off offset:-2048
	global_load_dwordx4 v[16:19], v[136:137], off offset:-1024
	global_load_dwordx4 v[12:15], v[136:137], off
	global_load_dwordx4 v[8:11], v[136:137], off offset:1024
	global_load_dwordx4 v[4:7], v[136:137], off offset:2048
	global_load_dwordx4 v[0:3], v[136:137], off offset:3072
	v_add_u32_e32 v33, 0xffffe000, v130
	v_lshrrev_b32_e32 v33, 3, v33
	v_ashrrev_i32_e32 v32, 12, v130
	v_add_u32_e32 v33, 2, v33
	v_cmp_gt_i32_e32 vcc, s3, v130
	s_nop 1
	v_cndmask_b32_e32 v32, v33, v32, vcc
	v_mad_i64_i32 v[64:65], s[26:27], v32, s18, v[138:139]
	v_add_co_u32_e32 v50, vcc, s19, v134
	v_lshl_add_u64 v[48:49], v[64:65], 0, s[12:13]
	s_nop 0
	v_addc_co_u32_e32 v51, vcc, -1, v135, vcc
	v_add_co_u32_e32 v60, vcc, s20, v134
	v_lshl_add_u64 v[40:41], v[48:49], 0, v[132:133]
	s_nop 0
	v_addc_co_u32_e32 v61, vcc, -1, v135, vcc
	v_add_co_u32_e32 v62, vcc, s21, v134
	v_lshl_add_u64 v[42:43], v[48:49], 0, v[140:141]
	v_lshl_add_u64 v[52:53], v[48:49], 0, v[142:143]
	v_lshl_add_u64 v[54:55], v[48:49], 0, v[144:145]
	v_addc_co_u32_e32 v63, vcc, -1, v135, vcc
	global_load_dwordx4 v[36:39], v[40:41], off
	global_load_dwordx4 v[32:35], v[42:43], off
	global_load_dwordx2 v[82:83], v[50:51], off offset:-3584
	global_load_dwordx2 v[84:85], v[50:51], off offset:-3072
	global_load_dwordx2 v[86:87], v[50:51], off offset:-2560
	global_load_dwordx2 v[88:89], v[50:51], off offset:-2048
	global_load_dwordx2 v[90:91], v[60:61], off offset:-3584
	global_load_dwordx2 v[92:93], v[60:61], off offset:-3072
	global_load_dwordx2 v[94:95], v[60:61], off offset:-2560
	global_load_dwordx2 v[96:97], v[60:61], off offset:-2048
	global_load_dwordx2 v[98:99], v[62:63], off offset:-3584
	global_load_dwordx2 v[100:101], v[62:63], off offset:-3072
	global_load_dwordx2 v[102:103], v[62:63], off offset:-2560
	global_load_dwordx2 v[104:105], v[62:63], off offset:-2048
	global_load_dwordx2 v[106:107], v[134:135], off offset:-3584
	global_load_dwordx2 v[108:109], v[134:135], off offset:-3072
	global_load_dwordx2 v[110:111], v[134:135], off offset:-2560
	global_load_dwordx2 v[112:113], v[134:135], off offset:-2048
	global_load_dwordx4 v[44:47], v[52:53], off
	global_load_dwordx4 v[40:43], v[54:55], off
	v_lshl_add_u64 v[52:53], v[48:49], 0, v[146:147]
	v_lshl_add_u64 v[54:55], v[48:49], 0, v[148:149]
	global_load_dwordx4 v[56:59], v[52:53], off
	s_nop 0
	global_load_dwordx4 v[52:55], v[54:55], off
	s_nop 0
	global_load_dwordx2 v[116:117], v[50:51], off offset:-1536
	global_load_dwordx2 v[118:119], v[50:51], off offset:-1024
	global_load_dwordx2 v[74:75], v[50:51], off offset:-512
	global_load_dwordx2 v[70:71], v[50:51], off
	global_load_dwordx2 v[120:121], v[60:61], off offset:-1536
	global_load_dwordx2 v[122:123], v[60:61], off offset:-1024
	global_load_dwordx2 v[80:81], v[60:61], off offset:-512
	global_load_dwordx2 v[72:73], v[60:61], off
	global_load_dwordx2 v[124:125], v[62:63], off offset:-1536
	global_load_dwordx2 v[126:127], v[62:63], off offset:-1024
	global_load_dwordx2 v[76:77], v[62:63], off offset:-512
	global_load_dwordx2 v[66:67], v[62:63], off
	global_load_dwordx2 v[172:173], v[134:135], off offset:-1536
	global_load_dwordx2 v[178:179], v[134:135], off offset:-1024
	global_load_dwordx2 v[78:79], v[134:135], off offset:-512
	global_load_dwordx2 v[68:69], v[134:135], off
	v_lshl_add_u64 v[114:115], v[48:49], 0, v[150:151]
	v_lshl_add_u64 v[48:49], v[48:49], 0, v[152:153]
	global_load_dwordx4 v[60:63], v[114:115], off
	s_nop 0
	global_load_dwordx4 v[48:51], v[48:49], off
	s_waitcnt vmcnt(37)
	v_lshlrev_b32_e32 v114, 16, v82
	v_and_b32_e32 v115, 0xffff0000, v82
	s_waitcnt vmcnt(33)
	v_lshlrev_b32_e32 v154, 16, v90
	v_and_b32_e32 v155, 0xffff0000, v90
	v_lshlrev_b32_e32 v82, 16, v83
	v_and_b32_e32 v83, 0xffff0000, v83
	v_lshlrev_b32_e32 v90, 16, v91
	v_and_b32_e32 v91, 0xffff0000, v91
	v_pk_add_f32 v[114:115], v[114:115], v[154:155]
	s_waitcnt vmcnt(29)
	v_lshlrev_b32_e32 v154, 16, v98
	v_and_b32_e32 v155, 0xffff0000, v98
	v_pk_add_f32 v[82:83], v[82:83], v[90:91]
	v_lshlrev_b32_e32 v90, 16, v99
	v_and_b32_e32 v91, 0xffff0000, v99
	s_waitcnt vmcnt(25)
	v_lshlrev_b32_e32 v98, 16, v107
	v_and_b32_e32 v99, 0xffff0000, v107
	v_lshlrev_b32_e32 v156, 16, v106
	v_and_b32_e32 v157, 0xffff0000, v106
	v_pk_add_f32 v[90:91], v[90:91], v[98:99]
	v_pk_add_f32 v[154:155], v[154:155], v[156:157]
	v_pk_add_f32 v[156:157], v[82:83], v[90:91]
	v_lshlrev_b32_e32 v82, 16, v84
	v_and_b32_e32 v83, 0xffff0000, v84
	v_lshlrev_b32_e32 v90, 16, v92
	v_and_b32_e32 v91, 0xffff0000, v92
	v_pk_add_f32 v[82:83], v[82:83], v[90:91]
	v_lshlrev_b32_e32 v90, 16, v100
	v_and_b32_e32 v91, 0xffff0000, v100
	s_waitcnt vmcnt(24)
	v_lshlrev_b32_e32 v98, 16, v108
	v_and_b32_e32 v99, 0xffff0000, v108
	v_pk_add_f32 v[90:91], v[90:91], v[98:99]
	v_lshlrev_b32_e32 v84, 16, v93
	v_pk_add_f32 v[158:159], v[82:83], v[90:91]
	v_lshlrev_b32_e32 v82, 16, v85
	v_and_b32_e32 v83, 0xffff0000, v85
	v_and_b32_e32 v85, 0xffff0000, v93
	v_pk_add_f32 v[82:83], v[82:83], v[84:85]
	v_lshlrev_b32_e32 v84, 16, v101
	v_and_b32_e32 v85, 0xffff0000, v101
	v_lshlrev_b32_e32 v90, 16, v109
	v_and_b32_e32 v91, 0xffff0000, v109
	v_pk_add_f32 v[84:85], v[84:85], v[90:91]
	s_waitcnt vmcnt(23)
	v_lshlrev_b32_e32 v90, 16, v110
	v_pk_add_f32 v[160:161], v[82:83], v[84:85]
	v_lshlrev_b32_e32 v82, 16, v86
	v_and_b32_e32 v83, 0xffff0000, v86
	v_lshlrev_b32_e32 v84, 16, v94
	v_and_b32_e32 v85, 0xffff0000, v94
	v_pk_add_f32 v[82:83], v[82:83], v[84:85]
	v_lshlrev_b32_e32 v84, 16, v102
	v_and_b32_e32 v85, 0xffff0000, v102
	v_and_b32_e32 v91, 0xffff0000, v110
	v_pk_add_f32 v[84:85], v[84:85], v[90:91]
	v_lshlrev_b32_e32 v86, 16, v111
	v_pk_add_f32 v[162:163], v[82:83], v[84:85]
	v_lshlrev_b32_e32 v82, 16, v87
	v_and_b32_e32 v83, 0xffff0000, v87
	v_lshlrev_b32_e32 v84, 16, v95
	v_and_b32_e32 v85, 0xffff0000, v95
	v_pk_add_f32 v[82:83], v[82:83], v[84:85]
	v_lshlrev_b32_e32 v84, 16, v103
	v_and_b32_e32 v85, 0xffff0000, v103
	v_and_b32_e32 v87, 0xffff0000, v111
	v_pk_add_f32 v[84:85], v[84:85], v[86:87]
	s_waitcnt vmcnt(22)
	v_lshlrev_b32_e32 v86, 16, v112
	v_pk_add_f32 v[164:165], v[82:83], v[84:85]
	v_mov_b32_e32 v84, v163
	v_mov_b32_e32 v85, v165
	v_mov_b32_e32 v82, v162
	v_mov_b32_e32 v83, v164
	v_pk_mul_f32 v[84:85], v[84:85], v[84:85]
	v_and_b32_e32 v87, 0xffff0000, v112
	v_pk_fma_f32 v[82:83], v[82:83], v[82:83], v[84:85]
	v_lshlrev_b32_e32 v84, 16, v96
	v_pk_add_f32 v[176:177], v[82:83], v[82:83] op_sel:[0,1] op_sel_hi:[1,0]
	v_lshlrev_b32_e32 v82, 16, v88
	v_and_b32_e32 v83, 0xffff0000, v88
	v_and_b32_e32 v85, 0xffff0000, v96
	v_pk_add_f32 v[82:83], v[82:83], v[84:85]
	v_lshlrev_b32_e32 v84, 16, v104
	v_and_b32_e32 v85, 0xffff0000, v104
	v_pk_add_f32 v[84:85], v[84:85], v[86:87]
	v_lshlrev_b32_e32 v86, 16, v113
	v_pk_add_f32 v[166:167], v[82:83], v[84:85]
	v_lshlrev_b32_e32 v82, 16, v89
	v_and_b32_e32 v83, 0xffff0000, v89
	v_lshlrev_b32_e32 v84, 16, v97
	v_and_b32_e32 v85, 0xffff0000, v97
	v_pk_add_f32 v[82:83], v[82:83], v[84:85]
	v_lshlrev_b32_e32 v84, 16, v105
	v_and_b32_e32 v85, 0xffff0000, v105
	v_and_b32_e32 v87, 0xffff0000, v113
	v_pk_add_f32 v[84:85], v[84:85], v[86:87]
	s_waitcnt vmcnt(5)
	v_lshlrev_b32_e32 v86, 16, v172
	v_pk_add_f32 v[168:169], v[82:83], v[84:85]
	v_mul_f32_e32 v82, v167, v167
	v_pk_fma_f32 v[190:191], v[166:167], v[166:167], v[82:83] op_sel_hi:[1,1,0]
	v_mul_f32_e32 v82, v169, v169
	v_pk_fma_f32 v[192:193], v[168:169], v[168:169], v[82:83] op_sel_hi:[1,1,0]
	v_lshlrev_b32_e32 v82, 16, v116
	v_and_b32_e32 v83, 0xffff0000, v116
	v_lshlrev_b32_e32 v84, 16, v120
	v_and_b32_e32 v85, 0xffff0000, v120
	v_pk_add_f32 v[82:83], v[82:83], v[84:85]
	v_lshlrev_b32_e32 v84, 16, v124
	v_and_b32_e32 v85, 0xffff0000, v124
	v_and_b32_e32 v87, 0xffff0000, v172
	v_pk_add_f32 v[84:85], v[84:85], v[86:87]
	v_lshlrev_b32_e32 v86, 16, v173
	v_pk_add_f32 v[170:171], v[82:83], v[84:85]
	v_lshlrev_b32_e32 v82, 16, v117
	v_and_b32_e32 v83, 0xffff0000, v117
	v_lshlrev_b32_e32 v84, 16, v121
	v_and_b32_e32 v85, 0xffff0000, v121
	v_pk_add_f32 v[82:83], v[82:83], v[84:85]
	v_lshlrev_b32_e32 v84, 16, v125
	v_and_b32_e32 v85, 0xffff0000, v125
	v_and_b32_e32 v87, 0xffff0000, v173
	v_pk_add_f32 v[84:85], v[84:85], v[86:87]
	s_waitcnt vmcnt(4)
	v_lshlrev_b32_e32 v86, 16, v178
	v_pk_add_f32 v[172:173], v[82:83], v[84:85]
	v_lshlrev_b32_e32 v82, 16, v118
	v_and_b32_e32 v83, 0xffff0000, v118
	v_lshlrev_b32_e32 v84, 16, v122
	v_and_b32_e32 v85, 0xffff0000, v122
	v_pk_add_f32 v[82:83], v[82:83], v[84:85]
	v_lshlrev_b32_e32 v84, 16, v126
	v_and_b32_e32 v85, 0xffff0000, v126
	v_and_b32_e32 v87, 0xffff0000, v178
	v_pk_add_f32 v[84:85], v[84:85], v[86:87]
	v_lshlrev_b32_e32 v86, 16, v179
	v_pk_add_f32 v[174:175], v[82:83], v[84:85]
	v_lshlrev_b32_e32 v82, 16, v119
	v_and_b32_e32 v83, 0xffff0000, v119
	v_lshlrev_b32_e32 v84, 16, v123
	v_and_b32_e32 v85, 0xffff0000, v123
	v_pk_add_f32 v[82:83], v[82:83], v[84:85]
	v_lshlrev_b32_e32 v84, 16, v127
	v_and_b32_e32 v85, 0xffff0000, v127
	v_and_b32_e32 v87, 0xffff0000, v179
	v_pk_add_f32 v[84:85], v[84:85], v[86:87]
	s_waitcnt vmcnt(3)
	v_lshlrev_b32_e32 v86, 16, v78
	v_pk_add_f32 v[178:179], v[82:83], v[84:85]
	v_mov_b32_e32 v84, v175
	v_mov_b32_e32 v85, v179
	v_mov_b32_e32 v82, v174
	v_mov_b32_e32 v83, v178
	v_pk_mul_f32 v[84:85], v[84:85], v[84:85]
	v_and_b32_e32 v87, 0xffff0000, v78
	v_pk_fma_f32 v[82:83], v[82:83], v[82:83], v[84:85]
	v_lshlrev_b32_e32 v84, 16, v80
	v_pk_add_f32 v[198:199], v[82:83], v[82:83] op_sel:[0,1] op_sel_hi:[1,0]
	v_lshlrev_b32_e32 v82, 16, v74
	v_and_b32_e32 v83, 0xffff0000, v74
	v_and_b32_e32 v85, 0xffff0000, v80
	v_pk_add_f32 v[82:83], v[82:83], v[84:85]
	v_lshlrev_b32_e32 v84, 16, v76
	v_and_b32_e32 v85, 0xffff0000, v76
	v_pk_add_f32 v[84:85], v[84:85], v[86:87]
	v_lshlrev_b32_e32 v74, 16, v75
	v_and_b32_e32 v75, 0xffff0000, v75
	v_lshlrev_b32_e32 v80, 16, v81
	v_and_b32_e32 v81, 0xffff0000, v81
	v_lshlrev_b32_e32 v76, 16, v77
	v_and_b32_e32 v77, 0xffff0000, v77
	v_lshlrev_b32_e32 v78, 16, v79
	v_and_b32_e32 v79, 0xffff0000, v79
	v_pk_add_f32 v[180:181], v[82:83], v[84:85]
	v_pk_add_f32 v[74:75], v[74:75], v[80:81]
	v_pk_add_f32 v[76:77], v[76:77], v[78:79]
	s_waitcnt vmcnt(2)
	v_lshlrev_b32_e32 v78, 16, v68
	v_pk_add_f32 v[182:183], v[74:75], v[76:77]
	v_mul_f32_e32 v74, v181, v181
	v_pk_fma_f32 v[200:201], v[180:181], v[180:181], v[74:75] op_sel_hi:[1,1,0]
	v_mul_f32_e32 v74, v183, v183
	v_pk_fma_f32 v[202:203], v[182:183], v[182:183], v[74:75] op_sel_hi:[1,1,0]
	v_lshlrev_b32_e32 v74, 16, v70
	v_and_b32_e32 v75, 0xffff0000, v70
	v_lshlrev_b32_e32 v76, 16, v72
	v_and_b32_e32 v77, 0xffff0000, v72
	v_pk_add_f32 v[74:75], v[74:75], v[76:77]
	v_lshlrev_b32_e32 v76, 16, v66
	v_and_b32_e32 v77, 0xffff0000, v66
	v_and_b32_e32 v79, 0xffff0000, v68
	v_lshlrev_b32_e32 v70, 16, v71
	v_and_b32_e32 v71, 0xffff0000, v71
	v_lshlrev_b32_e32 v72, 16, v73
	v_and_b32_e32 v73, 0xffff0000, v73
	v_lshlrev_b32_e32 v66, 16, v67
	v_and_b32_e32 v67, 0xffff0000, v67
	v_lshlrev_b32_e32 v68, 16, v69
	v_and_b32_e32 v69, 0xffff0000, v69
	v_pk_add_f32 v[76:77], v[76:77], v[78:79]
	v_pk_add_f32 v[70:71], v[70:71], v[72:73]
	v_pk_add_f32 v[66:67], v[66:67], v[68:69]
	v_pk_add_f32 v[204:205], v[74:75], v[76:77]
	v_pk_add_f32 v[206:207], v[70:71], v[66:67]
	v_pk_add_f32 v[154:155], v[114:115], v[154:155]
	v_pk_mul_f32 v[194:195], v[170:171], v[170:171]
	v_pk_mul_f32 v[196:197], v[172:173], v[172:173]
	v_pk_mul_f32 v[208:209], v[204:205], v[204:205]
	v_pk_mul_f32 v[210:211], v[206:207], v[206:207]
	v_lshl_add_u64 v[120:121], v[64:65], 0, s[14:15]
	v_lshl_add_u64 v[122:123], v[64:65], 0, s[16:17]
	v_lshl_add_u64 v[64:65], v[120:121], 0, v[132:133]
	v_lshl_add_u64 v[68:69], v[122:123], 0, v[132:133]
	v_lshl_add_u64 v[72:73], v[120:121], 0, v[140:141]
	v_lshl_add_u64 v[76:77], v[122:123], 0, v[140:141]
	v_lshl_add_u64 v[80:81], v[120:121], 0, v[142:143]
	v_lshl_add_u64 v[84:85], v[122:123], 0, v[142:143]
	v_lshl_add_u64 v[88:89], v[120:121], 0, v[144:145]
	v_lshl_add_u64 v[92:93], v[122:123], 0, v[144:145]
	v_lshl_add_u64 v[96:97], v[120:121], 0, v[146:147]
	v_lshl_add_u64 v[100:101], v[122:123], 0, v[146:147]
	v_lshl_add_u64 v[104:105], v[120:121], 0, v[148:149]
	v_lshl_add_u64 v[108:109], v[122:123], 0, v[148:149]
	v_lshl_add_u64 v[112:113], v[120:121], 0, v[150:151]
	v_lshl_add_u64 v[116:117], v[122:123], 0, v[150:151]
	v_lshl_add_u64 v[120:121], v[120:121], 0, v[152:153]
	v_lshl_add_u64 v[124:125], v[122:123], 0, v[152:153]
	global_load_dwordx4 v[64:67], v[64:65], off
	s_nop 0
	global_load_dwordx4 v[68:71], v[68:69], off
	s_nop 0
	global_load_dwordx4 v[72:75], v[72:73], off
	s_nop 0
	global_load_dwordx4 v[76:79], v[76:77], off
	s_nop 0
	global_load_dwordx4 v[80:83], v[80:81], off
	s_nop 0
	global_load_dwordx4 v[84:87], v[84:85], off
	s_nop 0
	global_load_dwordx4 v[88:91], v[88:89], off
	s_nop 0
	global_load_dwordx4 v[92:95], v[92:93], off
	s_nop 0
	global_load_dwordx4 v[96:99], v[96:97], off
	s_nop 0
	global_load_dwordx4 v[100:103], v[100:101], off
	s_nop 0
	global_load_dwordx4 v[104:107], v[104:105], off
	s_nop 0
	global_load_dwordx4 v[108:111], v[108:109], off
	s_nop 0
	global_load_dwordx4 v[112:115], v[112:113], off
	s_nop 0
	global_load_dwordx4 v[116:119], v[116:117], off
	s_nop 0
	global_load_dwordx4 v[120:123], v[120:121], off
	s_nop 0
	global_load_dwordx4 v[124:127], v[124:125], off
	v_mov_b32_e32 v216, v157
	v_mov_b32_e32 v217, v161
	v_mov_b32_e32 v212, v155
	v_mov_b32_e32 v213, v159
	v_mov_b32_e32 v214, v156
	v_mov_b32_e32 v215, v160
	v_pk_mul_f32 v[216:217], v[216:217], v[216:217]
	v_pk_mul_f32 v[212:213], v[212:213], v[212:213]
	v_pk_fma_f32 v[214:215], v[214:215], v[214:215], v[216:217]
	v_mov_b32_e32 v216, v154
	v_mov_b32_e32 v217, v158
	v_pk_fma_f32 v[212:213], v[216:217], v[216:217], v[212:213]
	v_mov_b32_e32 v191, v196
	v_pk_add_f32 v[212:213], v[212:213], v[214:215]
	v_mov_b32_e32 v193, v197
	v_pk_add_f32 v[212:213], v[212:213], v[212:213] op_sel:[0,1] op_sel_hi:[1,0]
	v_mov_b32_e32 v177, v195
	v_mov_b32_e32 v213, v194
	v_pk_add_f32 v[190:191], v[190:191], v[192:193]
	v_pk_add_f32 v[176:177], v[212:213], v[176:177]
	v_mov_b32_e32 v201, v210
	v_pk_add_f32 v[176:177], v[176:177], v[190:191]
	v_mov_b32_e32 v203, v211
	v_pk_add_f32 v[176:177], v[176:177], v[176:177] op_sel:[0,1] op_sel_hi:[1,0]
	v_mov_b32_e32 v199, v209
	v_mov_b32_e32 v177, v208
	v_pk_add_f32 v[190:191], v[200:201], v[202:203]
	v_pk_add_f32 v[176:177], v[176:177], v[198:199]
	s_nop 0
	v_pk_add_f32 v[176:177], v[176:177], v[190:191]
	s_nop 0
	v_add_f32_e32 v176, v176, v177
	ds_bpermute_b32 v177, v129, v176
	s_waitcnt lgkmcnt(0)
	v_add_f32_e32 v176, v176, v177
	ds_bpermute_b32 v177, v184, v176
	s_waitcnt lgkmcnt(0)
	v_add_f32_e32 v176, v176, v177
	ds_bpermute_b32 v177, v185, v176
	s_waitcnt lgkmcnt(0)
	v_add_f32_e32 v176, v176, v177
	ds_bpermute_b32 v177, v186, v176
	s_waitcnt lgkmcnt(0)
	v_add_f32_e32 v176, v176, v177
	ds_bpermute_b32 v177, v187, v176
	s_waitcnt lgkmcnt(0)
	v_add_f32_e32 v176, v176, v177
	ds_bpermute_b32 v177, v188, v176
	s_waitcnt lgkmcnt(0)
	v_add_f32_e32 v176, v176, v177
	v_fmamk_f32 v176, v176, 0x3a000000, v131
	v_mul_f32_e32 v177, 0x4b800000, v176
	v_cmp_gt_f32_e32 vcc, s22, v176
	s_nop 1
	v_cndmask_b32_e32 v176, v176, v177, vcc
	v_rsq_f32_e32 v176, v176
	s_nop 0
	v_mul_f32_e32 v177, 0x45800000, v176
	v_cndmask_b32_e32 v176, v176, v177, vcc
	v_pk_mul_f32 v[158:159], v[158:159], v[176:177] op_sel_hi:[1,0]
	v_pk_mul_f32 v[160:161], v[160:161], v[176:177] op_sel_hi:[1,0]
	v_pk_fma_f32 v[24:25], v[32:33], v[158:159], v[24:25]
	v_pk_fma_f32 v[26:27], v[34:35], v[160:161], v[26:27]
	v_pk_mul_f32 v[32:33], v[180:181], v[176:177] op_sel_hi:[1,0]
	v_pk_mul_f32 v[34:35], v[182:183], v[176:177] op_sel_hi:[1,0]
	v_pk_mul_f32 v[154:155], v[154:155], v[176:177] op_sel_hi:[1,0]
	v_pk_mul_f32 v[156:157], v[156:157], v[176:177] op_sel_hi:[1,0]
	s_waitcnt vmcnt(17)
	v_pk_fma_f32 v[6:7], v[62:63], v[34:35], v[6:7]
	v_pk_fma_f32 v[4:5], v[60:61], v[32:33], v[4:5]
	v_pk_mul_f32 v[32:33], v[204:205], v[176:177] op_sel_hi:[1,0]
	v_pk_mul_f32 v[34:35], v[206:207], v[176:177] op_sel_hi:[1,0]
	v_pk_mul_f32 v[162:163], v[162:163], v[176:177] op_sel_hi:[1,0]
	v_pk_mul_f32 v[164:165], v[164:165], v[176:177] op_sel_hi:[1,0]
	v_pk_mul_f32 v[166:167], v[166:167], v[176:177] op_sel_hi:[1,0]
	v_pk_mul_f32 v[168:169], v[168:169], v[176:177] op_sel_hi:[1,0]
	v_pk_mul_f32 v[170:171], v[170:171], v[176:177] op_sel_hi:[1,0]
	v_pk_mul_f32 v[172:173], v[172:173], v[176:177] op_sel_hi:[1,0]
	v_pk_mul_f32 v[174:175], v[174:175], v[176:177] op_sel_hi:[1,0]
	v_pk_mul_f32 v[178:179], v[178:179], v[176:177] op_sel_hi:[1,0]
	v_pk_fma_f32 v[30:31], v[38:39], v[156:157], v[30:31]
	v_pk_fma_f32 v[28:29], v[36:37], v[154:155], v[28:29]
	s_waitcnt vmcnt(16)
	v_pk_fma_f32 v[2:3], v[50:51], v[34:35], v[2:3]
	v_pk_fma_f32 v[0:1], v[48:49], v[32:33], v[0:1]
	v_pk_fma_f32 v[22:23], v[46:47], v[164:165], v[22:23]
	v_pk_fma_f32 v[20:21], v[44:45], v[162:163], v[20:21]
	v_pk_fma_f32 v[18:19], v[42:43], v[168:169], v[18:19]
	v_pk_fma_f32 v[16:17], v[40:41], v[166:167], v[16:17]
	v_pk_fma_f32 v[14:15], v[58:59], v[172:173], v[14:15]
	v_pk_fma_f32 v[12:13], v[56:57], v[170:171], v[12:13]
	v_pk_fma_f32 v[10:11], v[54:55], v[178:179], v[10:11]
	v_pk_fma_f32 v[8:9], v[52:53], v[174:175], v[8:9]
	global_store_dwordx4 v[136:137], v[28:31], off offset:-4096
	global_store_dwordx4 v[136:137], v[24:27], off offset:-3072
	global_store_dwordx4 v[136:137], v[20:23], off offset:-2048
	global_store_dwordx4 v[136:137], v[16:19], off offset:-1024
	global_store_dwordx4 v[136:137], v[12:15], off
	global_store_dwordx4 v[136:137], v[8:11], off offset:1024
	global_store_dwordx4 v[136:137], v[4:7], off offset:2048
	global_store_dwordx4 v[136:137], v[0:3], off offset:3072
	v_mov_b32_e32 v34, v29
	v_mov_b32_e32 v35, v25
	v_mov_b32_e32 v38, v31
	v_mov_b32_e32 v39, v27
	v_mov_b32_e32 v32, v28
	v_mov_b32_e32 v33, v24
	v_mov_b32_e32 v36, v30
	v_mov_b32_e32 v37, v26
	v_pk_mul_f32 v[40:41], v[22:23], v[22:23]
	v_pk_mul_f32 v[42:43], v[20:21], v[20:21]
	v_pk_mul_f32 v[34:35], v[34:35], v[34:35]
	v_pk_mul_f32 v[38:39], v[38:39], v[38:39]
	v_pk_mov_b32 v[58:59], v[42:43], v[40:41] op_sel:[1,0]
	v_mov_b32_e32 v43, v41
	v_pk_fma_f32 v[32:33], v[32:33], v[32:33], v[34:35]
	v_pk_fma_f32 v[34:35], v[36:37], v[36:37], v[38:39]
	v_mul_f32_e32 v44, v16, v16
	v_mul_f32_e32 v46, v18, v18
	v_pk_add_f32 v[36:37], v[58:59], v[42:43]
	v_pk_add_f32 v[32:33], v[32:33], v[34:35]
	v_pk_fma_f32 v[40:41], v[16:17], v[16:17], v[44:45] op_sel_hi:[1,1,0]
	v_pk_fma_f32 v[44:45], v[18:19], v[18:19], v[46:47] op_sel_hi:[1,1,0]
	v_pk_add_f32 v[34:35], v[36:37], v[36:37] op_sel_hi:[0,1]
	v_pk_add_f32 v[32:33], v[32:33], v[32:33] op_sel_hi:[0,1]
	v_pk_mul_f32 v[48:49], v[10:11], v[10:11]
	v_pk_mul_f32 v[50:51], v[8:9], v[8:9]
	v_mul_f32_e32 v40, v12, v12
	v_mul_f32_e32 v44, v13, v13
	v_mul_f32_e32 v34, v14, v14
	v_mul_f32_e32 v32, v15, v15
	v_pk_mov_b32 v[46:47], v[50:51], v[48:49] op_sel:[1,0]
	v_mov_b32_e32 v51, v49
	v_pk_add_f32 v[36:37], v[40:41], v[44:45]
	v_pk_add_f32 v[32:33], v[34:35], v[32:33]
	v_mul_f32_e32 v52, v4, v4
	v_mul_f32_e32 v54, v6, v6
	v_pk_add_f32 v[38:39], v[46:47], v[50:51]
	v_pk_add_f32 v[32:33], v[36:37], v[32:33]
	v_pk_fma_f32 v[48:49], v[4:5], v[4:5], v[52:53] op_sel_hi:[1,1,0]
	v_pk_fma_f32 v[52:53], v[6:7], v[6:7], v[54:55] op_sel_hi:[1,1,0]
	v_pk_add_f32 v[38:39], v[38:39], v[38:39] op_sel_hi:[0,1]
	v_pk_add_f32 v[32:33], v[32:33], v[32:33] op_sel_hi:[0,1]
	v_mul_f32_e32 v48, v0, v0
	v_mul_f32_e32 v52, v1, v1
	v_mul_f32_e32 v38, v2, v2
	v_mul_f32_e32 v32, v3, v3
	v_pk_add_f32 v[40:41], v[48:49], v[52:53]
	v_pk_add_f32 v[32:33], v[38:39], v[32:33]
	v_add_co_u32_e32 v56, vcc, s23, v134
	v_pk_add_f32 v[32:33], v[40:41], v[32:33]
	s_nop 0
	v_addc_co_u32_e32 v57, vcc, -1, v135, vcc
	v_add_f32_e32 v32, v32, v33
	ds_bpermute_b32 v33, v129, v32
	v_readfirstlane_b32 s83, v237
	s_add_u32 s83, s83, s94
	s_lshl_b32 s83, s83, 3
	s_sub_u32 s84, s83, s82
	s_mov_b32 s82, s83
	s_mov_b32 s85, 0
	s_mov_b32 s2, s84
	s_lshl_b64 s[6:7], s[84:85], 12
	s_lshl_b64 s[8:9], s[84:85], 13
	v_add_u32_e32 v130, s2, v130
	v_cmp_lt_i32_e32 vcc, s24, v130
	s_or_b64 s[10:11], vcc, s[10:11]
	v_lshl_add_u64 v[134:135], v[134:135], 0, s[6:7]
	s_waitcnt lgkmcnt(0)
	v_add_f32_e32 v32, v32, v33
	ds_bpermute_b32 v33, v184, v32
	v_lshl_add_u64 v[136:137], v[136:137], 0, s[8:9]
	s_waitcnt lgkmcnt(0)
	v_add_f32_e32 v32, v32, v33
	ds_bpermute_b32 v33, v185, v32
	s_waitcnt lgkmcnt(0)
	v_add_f32_e32 v32, v32, v33
	ds_bpermute_b32 v33, v186, v32
	s_waitcnt lgkmcnt(0)
	v_add_f32_e32 v32, v32, v33
	ds_bpermute_b32 v33, v187, v32
	s_waitcnt lgkmcnt(0)
	v_add_f32_e32 v32, v32, v33
	ds_bpermute_b32 v33, v188, v32
	s_waitcnt lgkmcnt(0)
	v_add_f32_e32 v32, v32, v33
	v_fmamk_f32 v32, v32, 0x3a000000, v131
	v_mul_f32_e32 v33, 0x4b800000, v32
	v_cmp_gt_f32_e32 vcc, s22, v32
	s_nop 1
	v_cndmask_b32_e32 v32, v32, v33, vcc
	v_rsq_f32_e32 v32, v32
	s_nop 0
	v_mul_f32_e32 v33, 0x45800000, v32
	v_cndmask_b32_e32 v32, v32, v33, vcc
	v_pk_mul_f32 v[28:29], v[28:29], v[32:33] op_sel_hi:[1,0]
	v_pk_mul_f32 v[30:31], v[30:31], v[32:33] op_sel_hi:[1,0]
	v_pk_mul_f32 v[24:25], v[24:25], v[32:33] op_sel_hi:[1,0]
	v_pk_mul_f32 v[26:27], v[26:27], v[32:33] op_sel_hi:[1,0]
	v_pk_mul_f32 v[20:21], v[20:21], v[32:33] op_sel_hi:[1,0]
	v_pk_mul_f32 v[22:23], v[22:23], v[32:33] op_sel_hi:[1,0]
	v_pk_mul_f32 v[16:17], v[16:17], v[32:33] op_sel_hi:[1,0]
	v_pk_mul_f32 v[18:19], v[18:19], v[32:33] op_sel_hi:[1,0]
	v_pk_mul_f32 v[12:13], v[12:13], v[32:33] op_sel_hi:[1,0]
	v_pk_mul_f32 v[14:15], v[14:15], v[32:33] op_sel_hi:[1,0]
	v_pk_mul_f32 v[8:9], v[8:9], v[32:33] op_sel_hi:[1,0]
	v_pk_mul_f32 v[10:11], v[10:11], v[32:33] op_sel_hi:[1,0]
	v_pk_mul_f32 v[4:5], v[4:5], v[32:33] op_sel_hi:[1,0]
	v_pk_mul_f32 v[6:7], v[6:7], v[32:33] op_sel_hi:[1,0]
	v_pk_mul_f32 v[0:1], v[0:1], v[32:33] op_sel_hi:[1,0]
	v_pk_mul_f32 v[2:3], v[2:3], v[32:33] op_sel_hi:[1,0]
	s_waitcnt vmcnt(22)
	v_pk_fma_f32 v[30:31], v[66:67], v[30:31], v[70:71]
	v_pk_fma_f32 v[28:29], v[64:65], v[28:29], v[68:69]
	s_waitcnt vmcnt(20)
	v_pk_fma_f32 v[26:27], v[74:75], v[26:27], v[78:79]
	v_pk_fma_f32 v[24:25], v[72:73], v[24:25], v[76:77]
	s_waitcnt vmcnt(18)
	v_pk_fma_f32 v[22:23], v[82:83], v[22:23], v[86:87]
	v_pk_fma_f32 v[20:21], v[80:81], v[20:21], v[84:85]
	s_waitcnt vmcnt(16)
	v_pk_fma_f32 v[18:19], v[90:91], v[18:19], v[94:95]
	v_pk_fma_f32 v[16:17], v[88:89], v[16:17], v[92:93]
	s_waitcnt vmcnt(14)
	v_pk_fma_f32 v[14:15], v[98:99], v[14:15], v[102:103]
	v_pk_fma_f32 v[12:13], v[96:97], v[12:13], v[100:101]
	s_waitcnt vmcnt(12)
	v_pk_fma_f32 v[10:11], v[106:107], v[10:11], v[110:111]
	v_pk_fma_f32 v[8:9], v[104:105], v[8:9], v[108:109]
	s_waitcnt vmcnt(10)
	v_pk_fma_f32 v[6:7], v[114:115], v[6:7], v[118:119]
	v_pk_fma_f32 v[4:5], v[112:113], v[4:5], v[116:117]
	s_waitcnt vmcnt(8)
	v_pk_fma_f32 v[2:3], v[122:123], v[2:3], v[126:127]
	v_pk_fma_f32 v[0:1], v[120:121], v[0:1], v[124:125]
	v_cvt_pk_bf16_f32 v28, v28, v29
	v_cvt_pk_bf16_f32 v29, v30, v31
	v_cvt_pk_bf16_f32 v24, v24, v25
	v_cvt_pk_bf16_f32 v25, v26, v27
	v_cvt_pk_bf16_f32 v20, v20, v21
	v_cvt_pk_bf16_f32 v21, v22, v23
	v_cvt_pk_bf16_f32 v16, v16, v17
	v_cvt_pk_bf16_f32 v17, v18, v19
	v_cvt_pk_bf16_f32 v12, v12, v13
	v_cvt_pk_bf16_f32 v13, v14, v15
	v_cvt_pk_bf16_f32 v8, v8, v9
	v_cvt_pk_bf16_f32 v9, v10, v11
	v_cvt_pk_bf16_f32 v4, v4, v5
	v_cvt_pk_bf16_f32 v5, v6, v7
	v_cvt_pk_bf16_f32 v0, v0, v1
	v_cvt_pk_bf16_f32 v1, v2, v3
	global_store_dwordx2 v[56:57], v[28:29], off offset:-3584
	global_store_dwordx2 v[56:57], v[24:25], off offset:-3072
	global_store_dwordx2 v[56:57], v[20:21], off offset:-2560
	global_store_dwordx2 v[56:57], v[16:17], off offset:-2048
	global_store_dwordx2 v[56:57], v[12:13], off offset:-1536
	global_store_dwordx2 v[56:57], v[8:9], off offset:-1024
	global_store_dwordx2 v[56:57], v[4:5], off offset:-512
	global_store_dwordx2 v[56:57], v[0:1], off
	s_andn2_b64 exec, exec, s[10:11]
	s_cbranch_execnz .LBB0_1625

.LBB0_1828:
	v_lshrrev_b32_e32 v0, 6, v128
	v_lshl_add_u32 v64, s34, 3, v0
	v_lshlrev_b32_e32 v236, 8, v0
	v_add_u32_e32 v236, 0x2c80, v236
	s_lshl_b32 s82, s34, 3
	s_movk_i32 s0, 0x2400
	v_cmp_gt_i32_e32 vcc, s0, v64
	s_and_saveexec_b64 s[0:1], vcc
	s_cbranch_execz .LBB0_1831
	v_mbcnt_lo_u32_b32 v1, -1, 0
	v_mbcnt_hi_u32_b32 v1, -1, v1
	s_waitcnt vmcnt(0)
	v_and_b32_e32 v2, 64, v1
	v_add_u32_e32 v2, 64, v2
	v_xor_b32_e32 v3, 1, v1
	v_cmp_lt_i32_e32 vcc, v3, v2
	v_ashrrev_i32_e32 v65, 31, v64
	v_lshlrev_b64 v[16:17], 12, v[64:65]
	v_cndmask_b32_e32 v3, v1, v3, vcc
	v_lshlrev_b32_e32 v130, 2, v3
	v_xor_b32_e32 v3, 2, v1
	v_cmp_lt_i32_e32 vcc, v3, v2
	s_mov_b64 s[2:3], 0x1ce05e00
	v_lshlrev_b32_e32 v0, 2, v128
	v_cndmask_b32_e32 v3, v1, v3, vcc
	v_lshlrev_b32_e32 v131, 2, v3
	v_xor_b32_e32 v3, 4, v1
	v_cmp_lt_i32_e32 vcc, v3, v2
	s_lshl_b32 s0, s94, 3
	v_and_b32_e32 v0, 0xfc, v0
	v_cndmask_b32_e32 v3, v1, v3, vcc
	v_lshlrev_b32_e32 v132, 2, v3
	v_xor_b32_e32 v3, 8, v1
	v_cmp_lt_i32_e32 vcc, v3, v2
	v_mov_b32_e32 v67, 0
	v_or_b32_e32 v4, 0x200, v0
	v_cndmask_b32_e32 v3, v1, v3, vcc
	v_lshlrev_b32_e32 v133, 2, v3
	v_xor_b32_e32 v3, 16, v1
	v_cmp_lt_i32_e32 vcc, v3, v2
	v_or_b32_e32 v6, 0x300, v0
	v_or_b32_e32 v8, 0x400, v0
	v_cndmask_b32_e32 v3, v1, v3, vcc
	v_lshlrev_b32_e32 v134, 2, v3
	v_xor_b32_e32 v3, 32, v1
	v_cmp_lt_i32_e32 vcc, v3, v2
	v_or_b32_e32 v2, 0x100, v0
	v_or_b32_e32 v10, 0x500, v0
	v_cndmask_b32_e32 v1, v1, v3, vcc
	v_lshlrev_b32_e32 v135, 2, v1
	v_and_b32_e32 v1, 63, v128
	v_lshl_or_b32 v16, v1, 3, v16
	v_lshl_add_u64 v[16:17], s[50:51], 0, v[16:17]
	v_lshl_add_u64 v[68:69], v[16:17], 0, s[2:3]
	v_lshlrev_b64 v[16:17], 13, v[64:65]
	v_lshl_or_b32 v16, v1, 4, v16
	v_or_b32_e32 v12, 0x600, v0
	v_or_b32_e32 v14, 0x700, v0
	s_ashr_i32 s1, s0, 31
	v_lshl_add_u64 v[16:17], s[48:49], 0, v[16:17]
	s_mov_b64 s[4:5], 0x1000
	s_lshl_b64 s[2:3], s[0:1], 12
	v_lshl_add_u64 v[70:71], v[16:17], 0, s[4:5]
	s_lshl_b64 s[4:5], s[0:1], 13
	s_mov_b64 s[6:7], 0
	s_movk_i32 s1, 0x2000
	s_mov_b32 s10, 0x12000
	v_mov_b64_e32 v[72:73], s[50:51]
	s_mov_b64 s[8:9], 0xc614000
	s_mov_b32 s11, 0xf3100000
	s_mov_b32 s12, 0xf5500000
	s_mov_b32 s13, 0xfdc00000
	v_lshlrev_b32_e32 v66, 2, v0
	v_lshlrev_b32_e32 v74, 2, v2
	v_mov_b32_e32 v75, v67
	v_lshlrev_b32_e32 v76, 2, v4
	v_mov_b32_e32 v77, v67
	v_lshlrev_b32_e32 v78, 2, v6
	v_mov_b32_e32 v79, v67
	v_lshlrev_b32_e32 v80, 2, v8
	v_mov_b32_e32 v81, v67
	v_lshlrev_b32_e32 v82, 2, v10
	v_mov_b32_e32 v83, v67
	v_lshlrev_b32_e32 v84, 2, v12
	v_mov_b32_e32 v85, v67
	v_lshlrev_b32_e32 v86, 2, v14
	v_mov_b32_e32 v87, v67
	v_mov_b32_e32 v65, 0x358637bd
	s_mov_b32 s14, 0x800000
	s_movk_i32 s15, 0x23ff
.LBB0_1830:
	s_mov_b64 s[80:81], exec
	s_mov_b64 exec, 1
	v_mov_b32_e32 v237, 1
	global_atomic_add v237, v236, v237, s[50:51] sc0
	s_mov_b64 exec, s[80:81]
	global_load_dwordx4 v[28:31], v[70:71], off offset:-4096
	global_load_dwordx4 v[24:27], v[70:71], off offset:-3072
	global_load_dwordx4 v[20:23], v[70:71], off offset:-2048
	global_load_dwordx4 v[16:19], v[70:71], off offset:-1024
	global_load_dwordx4 v[12:15], v[70:71], off
	global_load_dwordx4 v[8:11], v[70:71], off offset:1024
	global_load_dwordx4 v[4:7], v[70:71], off offset:2048
	global_load_dwordx4 v[0:3], v[70:71], off offset:3072
	v_add_u32_e32 v33, 0xffffe000, v64
	v_lshrrev_b32_e32 v33, 3, v33
	v_ashrrev_i32_e32 v32, 12, v64
	v_add_u32_e32 v33, 2, v33
	v_cmp_gt_i32_e32 vcc, s1, v64
	s_nop 1
	v_cndmask_b32_e32 v32, v33, v32, vcc
	v_mad_i64_i32 v[32:33], s[16:17], v32, s10, v[72:73]
	v_add_co_u32_e32 v50, vcc, s11, v68
	v_lshl_add_u64 v[48:49], v[32:33], 0, s[8:9]
	s_nop 0
	v_addc_co_u32_e32 v51, vcc, -1, v69, vcc
	v_add_co_u32_e32 v60, vcc, s12, v68
	v_lshl_add_u64 v[40:41], v[48:49], 0, v[66:67]
	s_nop 0
	v_addc_co_u32_e32 v61, vcc, -1, v69, vcc
	v_add_co_u32_e32 v62, vcc, s13, v68
	v_lshl_add_u64 v[42:43], v[48:49], 0, v[74:75]
	v_lshl_add_u64 v[52:53], v[48:49], 0, v[76:77]
	v_lshl_add_u64 v[54:55], v[48:49], 0, v[78:79]
	v_addc_co_u32_e32 v63, vcc, -1, v69, vcc
	global_load_dwordx4 v[36:39], v[40:41], off
	global_load_dwordx4 v[32:35], v[42:43], off
	global_load_dwordx2 v[90:91], v[50:51], off offset:-3584
	global_load_dwordx2 v[102:103], v[50:51], off offset:-3072
	global_load_dwordx2 v[114:115], v[50:51], off offset:-2560
	global_load_dwordx2 v[126:127], v[50:51], off offset:-2048
	global_load_dwordx2 v[100:101], v[60:61], off offset:-3584
	global_load_dwordx2 v[112:113], v[60:61], off offset:-3072
	global_load_dwordx2 v[116:117], v[60:61], off offset:-2560
	global_load_dwordx2 v[128:129], v[60:61], off offset:-2048
	global_load_dwordx2 v[136:137], v[62:63], off offset:-3584
	global_load_dwordx2 v[138:139], v[62:63], off offset:-3072
	global_load_dwordx2 v[140:141], v[62:63], off offset:-2560
	global_load_dwordx2 v[142:143], v[62:63], off offset:-2048
	global_load_dwordx2 v[144:145], v[68:69], off offset:-3584
	global_load_dwordx2 v[146:147], v[68:69], off offset:-3072
	global_load_dwordx2 v[148:149], v[68:69], off offset:-2560
	global_load_dwordx2 v[150:151], v[68:69], off offset:-2048
	global_load_dwordx4 v[44:47], v[52:53], off
	global_load_dwordx4 v[40:43], v[54:55], off
	v_lshl_add_u64 v[52:53], v[48:49], 0, v[80:81]
	v_lshl_add_u64 v[54:55], v[48:49], 0, v[82:83]
	global_load_dwordx4 v[56:59], v[52:53], off
	s_nop 0
	global_load_dwordx4 v[52:55], v[54:55], off
	s_nop 0
	global_load_dwordx2 v[152:153], v[50:51], off offset:-1536
	global_load_dwordx2 v[118:119], v[50:51], off offset:-1024
	global_load_dwordx2 v[104:105], v[50:51], off offset:-512
	global_load_dwordx2 v[96:97], v[50:51], off
	global_load_dwordx2 v[154:155], v[60:61], off offset:-1536
	global_load_dwordx2 v[124:125], v[60:61], off offset:-1024
	global_load_dwordx2 v[110:111], v[60:61], off offset:-512
	global_load_dwordx2 v[98:99], v[60:61], off
	global_load_dwordx2 v[156:157], v[62:63], off offset:-1536
	global_load_dwordx2 v[120:121], v[62:63], off offset:-1024
	global_load_dwordx2 v[106:107], v[62:63], off offset:-512
	global_load_dwordx2 v[92:93], v[62:63], off
	global_load_dwordx2 v[158:159], v[68:69], off offset:-1536
	global_load_dwordx2 v[122:123], v[68:69], off offset:-1024
	global_load_dwordx2 v[108:109], v[68:69], off offset:-512
	global_load_dwordx2 v[94:95], v[68:69], off
	v_lshl_add_u64 v[88:89], v[48:49], 0, v[84:85]
	v_lshl_add_u64 v[48:49], v[48:49], 0, v[86:87]
	global_load_dwordx4 v[60:63], v[88:89], off
	s_nop 0
	global_load_dwordx4 v[48:51], v[48:49], off
	s_waitcnt vmcnt(37)
	v_lshlrev_b32_e32 v88, 16, v90
	v_and_b32_e32 v89, 0xffff0000, v90
	s_waitcnt vmcnt(33)
	v_lshlrev_b32_e32 v160, 16, v100
	v_and_b32_e32 v161, 0xffff0000, v100
	v_lshlrev_b32_e32 v90, 16, v91
	v_and_b32_e32 v91, 0xffff0000, v91
	v_lshlrev_b32_e32 v100, 16, v101
	v_and_b32_e32 v101, 0xffff0000, v101
	v_pk_add_f32 v[88:89], v[88:89], v[160:161]
	s_waitcnt vmcnt(29)
	v_lshlrev_b32_e32 v160, 16, v136
	v_and_b32_e32 v161, 0xffff0000, v136
	v_pk_add_f32 v[90:91], v[90:91], v[100:101]
	v_lshlrev_b32_e32 v100, 16, v137
	v_and_b32_e32 v101, 0xffff0000, v137
	s_waitcnt vmcnt(25)
	v_lshlrev_b32_e32 v136, 16, v145
	v_and_b32_e32 v137, 0xffff0000, v145
	v_pk_add_f32 v[100:101], v[100:101], v[136:137]
	v_lshlrev_b32_e32 v136, 16, v112
	v_pk_add_f32 v[90:91], v[90:91], v[100:101]
	v_lshlrev_b32_e32 v100, 16, v102
	v_and_b32_e32 v101, 0xffff0000, v102
	v_and_b32_e32 v137, 0xffff0000, v112
	v_lshlrev_b32_e32 v162, 16, v144
	v_and_b32_e32 v163, 0xffff0000, v144
	v_pk_add_f32 v[100:101], v[100:101], v[136:137]
	v_lshlrev_b32_e32 v136, 16, v138
	v_and_b32_e32 v137, 0xffff0000, v138
	s_waitcnt vmcnt(24)
	v_lshlrev_b32_e32 v144, 16, v146
	v_and_b32_e32 v145, 0xffff0000, v146
	v_pk_add_f32 v[136:137], v[136:137], v[144:145]
	v_lshlrev_b32_e32 v102, 16, v103
	v_and_b32_e32 v103, 0xffff0000, v103
	v_lshlrev_b32_e32 v112, 16, v113
	v_and_b32_e32 v113, 0xffff0000, v113
	v_pk_add_f32 v[160:161], v[160:161], v[162:163]
	v_pk_add_f32 v[100:101], v[100:101], v[136:137]
	v_pk_add_f32 v[102:103], v[102:103], v[112:113]
	v_lshlrev_b32_e32 v112, 16, v139
	v_and_b32_e32 v113, 0xffff0000, v139
	v_lshlrev_b32_e32 v136, 16, v147
	v_and_b32_e32 v137, 0xffff0000, v147
	v_pk_add_f32 v[88:89], v[88:89], v[160:161]
	v_pk_add_f32 v[112:113], v[112:113], v[136:137]
	v_mov_b32_e32 v136, v89
	v_pk_add_f32 v[102:103], v[102:103], v[112:113]
	v_mov_b32_e32 v137, v101
	v_mov_b32_e32 v112, v88
	v_mov_b32_e32 v113, v100
	v_pk_mul_f32 v[136:137], v[136:137], v[136:137]
	v_mov_b32_e32 v138, v91
	v_mov_b32_e32 v139, v103
	v_pk_fma_f32 v[112:113], v[112:113], v[112:113], v[136:137]
	v_mov_b32_e32 v136, v90
	v_mov_b32_e32 v137, v102
	v_pk_mul_f32 v[138:139], v[138:139], v[138:139]
	s_waitcnt vmcnt(23)
	v_lshlrev_b32_e32 v144, 16, v148
	v_pk_fma_f32 v[136:137], v[136:137], v[136:137], v[138:139]
	v_lshlrev_b32_e32 v138, 16, v116
	v_pk_add_f32 v[112:113], v[112:113], v[136:137]
	v_and_b32_e32 v139, 0xffff0000, v116
	v_pk_add_f32 v[136:137], v[112:113], v[112:113] op_sel:[0,1] op_sel_hi:[1,0]
	v_lshlrev_b32_e32 v112, 16, v114
	v_and_b32_e32 v113, 0xffff0000, v114
	v_pk_add_f32 v[112:113], v[112:113], v[138:139]
	v_lshlrev_b32_e32 v138, 16, v140
	v_and_b32_e32 v139, 0xffff0000, v140
	v_and_b32_e32 v145, 0xffff0000, v148
	v_pk_add_f32 v[138:139], v[138:139], v[144:145]
	v_lshlrev_b32_e32 v114, 16, v115
	v_and_b32_e32 v115, 0xffff0000, v115
	v_lshlrev_b32_e32 v116, 16, v117
	v_and_b32_e32 v117, 0xffff0000, v117
	v_pk_add_f32 v[112:113], v[112:113], v[138:139]
	v_pk_add_f32 v[114:115], v[114:115], v[116:117]
	v_lshlrev_b32_e32 v116, 16, v141
	v_and_b32_e32 v117, 0xffff0000, v141
	v_lshlrev_b32_e32 v138, 16, v149
	v_and_b32_e32 v139, 0xffff0000, v149
	v_pk_add_f32 v[116:117], v[116:117], v[138:139]
	v_mov_b32_e32 v138, v113
	v_pk_add_f32 v[114:115], v[114:115], v[116:117]
	v_mov_b32_e32 v116, v112
	v_mov_b32_e32 v139, v115
	v_mov_b32_e32 v117, v114
	v_pk_mul_f32 v[138:139], v[138:139], v[138:139]
	v_lshlrev_b32_e32 v140, 16, v128
	v_pk_fma_f32 v[116:117], v[116:117], v[116:117], v[138:139]
	v_and_b32_e32 v141, 0xffff0000, v128
	v_pk_add_f32 v[138:139], v[116:117], v[116:117] op_sel:[0,1] op_sel_hi:[1,0]
	v_lshlrev_b32_e32 v116, 16, v126
	v_and_b32_e32 v117, 0xffff0000, v126
	v_pk_add_f32 v[116:117], v[116:117], v[140:141]
	v_lshlrev_b32_e32 v140, 16, v142
	v_and_b32_e32 v141, 0xffff0000, v142
	s_waitcnt vmcnt(22)
	v_lshlrev_b32_e32 v144, 16, v150
	v_and_b32_e32 v145, 0xffff0000, v150
	v_pk_add_f32 v[140:141], v[140:141], v[144:145]
	v_lshlrev_b32_e32 v126, 16, v127
	v_and_b32_e32 v127, 0xffff0000, v127
	v_lshlrev_b32_e32 v128, 16, v129
	v_and_b32_e32 v129, 0xffff0000, v129
	v_pk_add_f32 v[116:117], v[116:117], v[140:141]
	v_pk_add_f32 v[126:127], v[126:127], v[128:129]
	v_lshlrev_b32_e32 v128, 16, v143
	v_and_b32_e32 v129, 0xffff0000, v143
	v_lshlrev_b32_e32 v140, 16, v151
	v_and_b32_e32 v141, 0xffff0000, v151
	v_pk_add_f32 v[128:129], v[128:129], v[140:141]
	s_waitcnt vmcnt(13)
	v_lshlrev_b32_e32 v144, 16, v154
	v_pk_add_f32 v[126:127], v[126:127], v[128:129]
	v_mul_f32_e32 v128, v117, v117
	v_pk_fma_f32 v[140:141], v[116:117], v[116:117], v[128:129] op_sel_hi:[1,1,0]
	v_mul_f32_e32 v128, v127, v127
	v_pk_fma_f32 v[142:143], v[126:127], v[126:127], v[128:129] op_sel_hi:[1,1,0]
	v_lshlrev_b32_e32 v128, 16, v152
	v_and_b32_e32 v129, 0xffff0000, v152
	v_and_b32_e32 v145, 0xffff0000, v154
	v_pk_add_f32 v[128:129], v[128:129], v[144:145]
	s_waitcnt vmcnt(9)
	v_lshlrev_b32_e32 v144, 16, v156
	v_and_b32_e32 v145, 0xffff0000, v156
	s_waitcnt vmcnt(5)
	v_lshlrev_b32_e32 v146, 16, v158
	v_and_b32_e32 v147, 0xffff0000, v158
	v_pk_add_f32 v[144:145], v[144:145], v[146:147]
	v_lshlrev_b32_e32 v146, 16, v155
	v_pk_add_f32 v[128:129], v[128:129], v[144:145]
	v_lshlrev_b32_e32 v144, 16, v153
	v_and_b32_e32 v145, 0xffff0000, v153
	v_and_b32_e32 v147, 0xffff0000, v155
	v_pk_add_f32 v[144:145], v[144:145], v[146:147]
	v_lshlrev_b32_e32 v146, 16, v157
	v_and_b32_e32 v147, 0xffff0000, v157
	v_lshlrev_b32_e32 v148, 16, v159
	v_and_b32_e32 v149, 0xffff0000, v159
	v_pk_add_f32 v[146:147], v[146:147], v[148:149]
	s_nop 0
	v_pk_add_f32 v[144:145], v[144:145], v[146:147]
	v_pk_mul_f32 v[146:147], v[128:129], v[128:129]
	v_pk_mul_f32 v[148:149], v[144:145], v[144:145]
	v_mov_b32_e32 v137, v146
	v_mov_b32_e32 v139, v147
	v_mov_b32_e32 v141, v148
	v_mov_b32_e32 v143, v149
	v_pk_add_f32 v[136:137], v[136:137], v[138:139]
	v_pk_add_f32 v[138:139], v[140:141], v[142:143]
	v_lshlrev_b32_e32 v140, 16, v124
	v_pk_add_f32 v[136:137], v[136:137], v[138:139]
	v_lshlrev_b32_e32 v138, 16, v118
	v_and_b32_e32 v139, 0xffff0000, v118
	v_and_b32_e32 v141, 0xffff0000, v124
	v_pk_add_f32 v[138:139], v[138:139], v[140:141]
	v_lshlrev_b32_e32 v140, 16, v120
	v_and_b32_e32 v141, 0xffff0000, v120
	s_waitcnt vmcnt(4)
	v_lshlrev_b32_e32 v142, 16, v122
	v_and_b32_e32 v143, 0xffff0000, v122
	v_lshlrev_b32_e32 v118, 16, v119
	v_and_b32_e32 v119, 0xffff0000, v119
	v_lshlrev_b32_e32 v124, 16, v125
	v_and_b32_e32 v125, 0xffff0000, v125
	v_lshlrev_b32_e32 v120, 16, v121
	v_and_b32_e32 v121, 0xffff0000, v121
	v_lshlrev_b32_e32 v122, 16, v123
	v_and_b32_e32 v123, 0xffff0000, v123
	v_pk_add_f32 v[140:141], v[140:141], v[142:143]
	v_pk_add_f32 v[118:119], v[118:119], v[124:125]
	v_pk_add_f32 v[120:121], v[120:121], v[122:123]
	v_pk_add_f32 v[138:139], v[138:139], v[140:141]
	v_pk_add_f32 v[118:119], v[118:119], v[120:121]
	v_mov_b32_e32 v122, v139
	v_mov_b32_e32 v123, v119
	v_mov_b32_e32 v120, v138
	v_mov_b32_e32 v121, v118
	v_pk_mul_f32 v[122:123], v[122:123], v[122:123]
	v_lshlrev_b32_e32 v124, 16, v110
	v_pk_fma_f32 v[120:121], v[120:121], v[120:121], v[122:123]
	v_lshlrev_b32_e32 v122, 16, v104
	v_and_b32_e32 v123, 0xffff0000, v104
	v_and_b32_e32 v125, 0xffff0000, v110
	v_pk_add_f32 v[122:123], v[122:123], v[124:125]
	v_lshlrev_b32_e32 v124, 16, v106
	v_and_b32_e32 v125, 0xffff0000, v106
	s_waitcnt vmcnt(3)
	v_lshlrev_b32_e32 v140, 16, v108
	v_and_b32_e32 v141, 0xffff0000, v108
	v_pk_add_f32 v[124:125], v[124:125], v[140:141]
	v_lshlrev_b32_e32 v104, 16, v105
	v_and_b32_e32 v105, 0xffff0000, v105
	v_lshlrev_b32_e32 v110, 16, v111
	v_and_b32_e32 v111, 0xffff0000, v111
	v_pk_add_f32 v[122:123], v[122:123], v[124:125]
	v_pk_add_f32 v[104:105], v[104:105], v[110:111]
	v_lshlrev_b32_e32 v106, 16, v107
	v_and_b32_e32 v107, 0xffff0000, v107
	v_lshlrev_b32_e32 v108, 16, v109
	v_and_b32_e32 v109, 0xffff0000, v109
	v_lshlrev_b32_e32 v110, 16, v96
	v_and_b32_e32 v111, 0xffff0000, v96
	v_lshlrev_b32_e32 v124, 16, v98
	v_and_b32_e32 v125, 0xffff0000, v98
	v_pk_add_f32 v[106:107], v[106:107], v[108:109]
	v_pk_add_f32 v[110:111], v[110:111], v[124:125]
	v_lshlrev_b32_e32 v124, 16, v92
	v_and_b32_e32 v125, 0xffff0000, v92
	s_waitcnt vmcnt(2)
	v_lshlrev_b32_e32 v140, 16, v94
	v_and_b32_e32 v141, 0xffff0000, v94
	v_lshlrev_b32_e32 v96, 16, v97
	v_and_b32_e32 v97, 0xffff0000, v97
	v_lshlrev_b32_e32 v98, 16, v99
	v_and_b32_e32 v99, 0xffff0000, v99
	v_lshlrev_b32_e32 v92, 16, v93
	v_and_b32_e32 v93, 0xffff0000, v93
	v_lshlrev_b32_e32 v94, 16, v95
	v_and_b32_e32 v95, 0xffff0000, v95
	v_pk_add_f32 v[104:105], v[104:105], v[106:107]
	v_pk_add_f32 v[124:125], v[124:125], v[140:141]
	v_pk_add_f32 v[96:97], v[96:97], v[98:99]
	v_pk_add_f32 v[92:93], v[92:93], v[94:95]
	v_mul_f32_e32 v106, v123, v123
	v_mul_f32_e32 v108, v105, v105
	v_pk_add_f32 v[110:111], v[110:111], v[124:125]
	v_pk_add_f32 v[92:93], v[96:97], v[92:93]
	v_pk_add_f32 v[136:137], v[136:137], v[136:137] op_sel:[0,1] op_sel_hi:[1,0]
	v_pk_add_f32 v[120:121], v[120:121], v[120:121] op_sel:[0,1] op_sel_hi:[1,0]
	v_pk_fma_f32 v[106:107], v[122:123], v[122:123], v[106:107] op_sel_hi:[1,1,0]
	v_pk_fma_f32 v[108:109], v[104:105], v[104:105], v[108:109] op_sel_hi:[1,1,0]
	v_pk_mul_f32 v[94:95], v[110:111], v[110:111]
	v_pk_mul_f32 v[96:97], v[92:93], v[92:93]
	v_mov_b32_e32 v137, v94
	v_mov_b32_e32 v121, v95
	v_mov_b32_e32 v107, v96
	v_mov_b32_e32 v109, v97
	v_pk_add_f32 v[94:95], v[136:137], v[120:121]
	v_pk_add_f32 v[96:97], v[106:107], v[108:109]
	s_nop 0
	v_pk_add_f32 v[94:95], v[94:95], v[96:97]
	s_nop 0
	v_add_f32_e32 v94, v94, v95
	ds_bpermute_b32 v95, v130, v94
	s_waitcnt lgkmcnt(0)
	v_add_f32_e32 v94, v94, v95
	ds_bpermute_b32 v95, v131, v94
	s_waitcnt lgkmcnt(0)
	v_add_f32_e32 v94, v94, v95
	ds_bpermute_b32 v95, v132, v94
	s_waitcnt lgkmcnt(0)
	v_add_f32_e32 v94, v94, v95
	ds_bpermute_b32 v95, v133, v94
	s_waitcnt lgkmcnt(0)
	v_add_f32_e32 v94, v94, v95
	ds_bpermute_b32 v95, v134, v94
	s_waitcnt lgkmcnt(0)
	v_add_f32_e32 v94, v94, v95
	ds_bpermute_b32 v95, v135, v94
	s_waitcnt lgkmcnt(0)
	v_add_f32_e32 v94, v94, v95
	v_fmamk_f32 v94, v94, 0x3a000000, v65
	v_mul_f32_e32 v95, 0x4b800000, v94
	v_cmp_gt_f32_e32 vcc, s14, v94
	s_nop 1
	v_cndmask_b32_e32 v94, v94, v95, vcc
	v_rsq_f32_e32 v94, v94
	s_nop 0
	v_mul_f32_e32 v95, 0x45800000, v94
	v_cndmask_b32_e32 v94, v94, v95, vcc
	v_pk_mul_f32 v[88:89], v[88:89], v[94:95] op_sel_hi:[1,0]
	v_pk_mul_f32 v[90:91], v[90:91], v[94:95] op_sel_hi:[1,0]
	v_pk_mul_f32 v[106:107], v[116:117], v[94:95] op_sel_hi:[1,0]
	v_pk_mul_f32 v[116:117], v[138:139], v[94:95] op_sel_hi:[1,0]
	v_pk_mul_f32 v[118:119], v[118:119], v[94:95] op_sel_hi:[1,0]
	v_pk_mul_f32 v[96:97], v[100:101], v[94:95] op_sel_hi:[1,0]
	v_pk_mul_f32 v[98:99], v[102:103], v[94:95] op_sel_hi:[1,0]
	v_pk_mul_f32 v[100:101], v[112:113], v[94:95] op_sel_hi:[1,0]
	v_pk_mul_f32 v[102:103], v[114:115], v[94:95] op_sel_hi:[1,0]
	v_pk_mul_f32 v[108:109], v[126:127], v[94:95] op_sel_hi:[1,0]
	v_pk_mul_f32 v[112:113], v[128:129], v[94:95] op_sel_hi:[1,0]
	v_pk_mul_f32 v[114:115], v[144:145], v[94:95] op_sel_hi:[1,0]
	v_pk_fma_f32 v[30:31], v[38:39], v[90:91], v[30:31]
	v_pk_fma_f32 v[28:29], v[36:37], v[88:89], v[28:29]
	v_pk_fma_f32 v[10:11], v[54:55], v[118:119], v[10:11]
	v_pk_fma_f32 v[8:9], v[52:53], v[116:117], v[8:9]
	v_pk_fma_f32 v[26:27], v[34:35], v[98:99], v[26:27]
	v_pk_fma_f32 v[24:25], v[32:33], v[96:97], v[24:25]
	v_pk_fma_f32 v[22:23], v[46:47], v[102:103], v[22:23]
	v_pk_fma_f32 v[20:21], v[44:45], v[100:101], v[20:21]
	v_pk_fma_f32 v[18:19], v[42:43], v[108:109], v[18:19]
	v_pk_fma_f32 v[16:17], v[40:41], v[106:107], v[16:17]
	v_pk_fma_f32 v[14:15], v[58:59], v[114:115], v[14:15]
	v_pk_fma_f32 v[12:13], v[56:57], v[112:113], v[12:13]
	global_store_dwordx4 v[70:71], v[28:31], off offset:-4096
	global_store_dwordx4 v[70:71], v[24:27], off offset:-3072
	global_store_dwordx4 v[70:71], v[20:23], off offset:-2048
	global_store_dwordx4 v[70:71], v[16:19], off offset:-1024
	global_store_dwordx4 v[70:71], v[12:15], off
	global_store_dwordx4 v[70:71], v[8:11], off offset:1024
	s_nop 1
	v_pk_mul_f32 v[8:9], v[122:123], v[94:95] op_sel_hi:[1,0]
	v_pk_mul_f32 v[10:11], v[104:105], v[94:95] op_sel_hi:[1,0]
	s_waitcnt vmcnt(7)
	v_pk_fma_f32 v[4:5], v[60:61], v[8:9], v[4:5]
	v_pk_fma_f32 v[6:7], v[62:63], v[10:11], v[6:7]
	global_store_dwordx4 v[70:71], v[4:7], off offset:2048
	s_nop 1
	v_pk_mul_f32 v[4:5], v[110:111], v[94:95] op_sel_hi:[1,0]
	v_pk_mul_f32 v[6:7], v[92:93], v[94:95] op_sel_hi:[1,0]
	s_waitcnt vmcnt(7)
	v_pk_fma_f32 v[0:1], v[48:49], v[4:5], v[0:1]
	v_pk_fma_f32 v[2:3], v[50:51], v[6:7], v[2:3]
	global_store_dwordx4 v[70:71], v[0:3], off offset:3072
	s_waitcnt vmcnt(8)
	v_readfirstlane_b32 s83, v237
	s_add_u32 s83, s83, s94
	s_lshl_b32 s83, s83, 3
	s_sub_u32 s84, s83, s82
	s_mov_b32 s82, s83
	s_mov_b32 s85, 0
	s_mov_b32 s0, s84
	s_lshl_b64 s[2:3], s[84:85], 12
	s_lshl_b64 s[4:5], s[84:85], 13
	v_add_u32_e32 v64, s0, v64
	v_cmp_lt_i32_e32 vcc, s15, v64
	v_lshl_add_u64 v[68:69], v[68:69], 0, s[2:3]
	s_or_b64 s[6:7], vcc, s[6:7]
	v_lshl_add_u64 v[70:71], v[70:71], 0, s[4:5]
	s_andn2_b64 exec, exec, s[6:7]
	s_cbranch_execnz .LBB0_1830
